# stack42 with an 8-level finer GEMM phase stagger ((blockIdx>>3)&7 x s_sleep 0x15)
# speedup vs baseline: 1.0051x; 1.0051x over previous
.LBB0_147:
	s_cmp_lt_i32 s92, 2
	s_cselect_b64 s[4:5], -1, 0
	s_and_b64 s[4:5], s[4:5], s[2:3]
	s_andn2_b64 vcc, exec, s[4:5]
	s_cbranch_vccnz .LBB0_166
	s_mov_b32 s2, 0
	s_ashr_i32 s3, s2, 31
	s_add_u32 s2, s0, s2
	s_addc_u32 s3, s1, s3
	s_load_dwordx2 s[2:3], s[2:3], 0xc0
	s_bfe_u32 s6, s10, 0x30003
	s_cmp_eq_u32 s6, 0
	s_cbranch_scc1 .LBB0_150

.LBB0_222:
	s_cmp_lt_i32 s92, 3
	s_cselect_b64 s[4:5], -1, 0
	s_and_b64 s[16:17], s[4:5], s[2:3]
	s_andn2_b64 vcc, exec, s[16:17]
	s_cbranch_vccnz .LBB0_319
	s_mov_b32 s2, 0
	s_ashr_i32 s3, s2, 31
	s_add_u32 s2, s0, s2
	s_addc_u32 s3, s1, s3
	s_load_dwordx4 s[12:15], s[2:3], 0xb8
	s_load_dwordx2 s[18:19], s[2:3], 0x0
	s_bfe_u32 s2, s10, 0x30003
	s_cmp_eq_u32 s2, 0
	s_cbranch_scc1 .LBB0_225

.LBB0_375:
	s_cmp_lt_i32 s92, 4
	s_cselect_b64 s[4:5], -1, 0
	s_and_b64 s[8:9], s[4:5], s[2:3]
	s_andn2_b64 vcc, exec, s[8:9]
	s_cbranch_vccnz .LBB0_436
	s_mov_b32 s21, 0
	s_ashr_i32 s23, s21, 31
	s_add_u32 s2, s0, s21
	s_addc_u32 s3, s1, s23
	s_waitcnt lgkmcnt(0)
	s_load_dwordx2 s[12:13], s[2:3], 0xc0
	s_bfe_u32 s2, s10, 0x30003
	s_cmp_eq_u32 s2, 0
	s_cbranch_scc1 .LBB0_378

.LBB0_1095:
	s_cmp_lt_i32 s92, 9
	s_cselect_b64 s[4:5], -1, 0
	s_and_b64 s[8:9], s[4:5], s[2:3]
	s_andn2_b64 vcc, exec, s[8:9]
	s_cbranch_vccnz .LBB0_1172
	s_mov_b32 s2, 0
	s_ashr_i32 s3, s2, 31
	s_add_u32 s2, s0, s2
	s_addc_u32 s3, s1, s3
	s_waitcnt lgkmcnt(0)
	s_load_dwordx4 s[12:15], s[2:3], 0xb8
	s_bfe_u32 s2, s10, 0x30003
	s_cmp_eq_u32 s2, 0
	s_cbranch_scc1 .LBB0_1098

.LBB0_1228:
	s_cmp_lt_i32 s92, 10
	s_cselect_b64 s[4:5], -1, 0
	s_and_b64 s[4:5], s[4:5], s[2:3]
	s_andn2_b64 vcc, exec, s[4:5]
	s_cbranch_vccnz .LBB0_1247
	s_mov_b32 s2, 0
	s_ashr_i32 s3, s2, 31
	s_add_u32 s2, s0, s2
	s_addc_u32 s3, s1, s3
	s_load_dwordx2 s[2:3], s[2:3], 0xc0
	s_bfe_u32 s6, s10, 0x30003
	s_cmp_eq_u32 s6, 0
	s_cbranch_scc1 .LBB0_1231

.LBB0_1303:
	s_cmp_lt_i32 s92, 11
	s_cselect_b64 s[4:5], -1, 0
	s_and_b64 s[6:7], s[4:5], s[2:3]
	s_andn2_b64 vcc, exec, s[6:7]
	s_cbranch_vccnz .LBB0_1336
	s_mov_b32 s2, 0
	s_ashr_i32 s3, s2, 31
	s_add_u32 s2, s0, s2
	s_addc_u32 s3, s1, s3
	s_load_dwordx4 s[12:15], s[2:3], 0xb8
	s_bfe_u32 s2, s10, 0x30003
	s_cmp_eq_u32 s2, 0
	s_cbranch_scc1 .LBB0_1306
